# speedup vs baseline: 1.0170x; 1.0058x over previous
; template <int KS, bool SAFE> __device__ __forceinline__ void fused_ks(f32x16* o, f32x16& lacc, int vb, const VFrag& cur, VFrag& nxt, f32x16& p0, f32x16& p1, float& ps, ...
;   if constexpr (KS < 3) { vfrag_issue<KS + 1>(nxt, vb); asm volatile("s_waitcnt lgkmcnt(8)" ::: "memory"); }
;   else asm volatile("s_waitcnt lgkmcnt(0)" ::: "memory");
;   const bf16x8 pa = (KS == 0) ? pa0 : (KS == 1) ? pa1 : (KS == 2) ? pa2 : pa3;
;   SBAR();
;   o[0] = MFMA32(pa, PKV(cur.l0, cur.h0), o[0]); SBAR(); sm1_chunk<KS * 4 + 0>(p0, p1); if constexpr (KS > 0) SM2_UNIT(2 * KS - 1); SBAR();
;   o[1] = MFMA32(pa, PKV(cur.l1, cur.h1), o[1]); SBAR(); sm1_chunk<KS * 4 + 1>(p0, p1);
;   if (dow) {
;     if constexpr (KS == 0) { asm volatile("s_waitcnt vmcnt(0)" ::: "memory"); *reinterpret_cast<bf16x8*>(sd.k0) = st.ks0; }
;     else if constexpr (KS == 1) *reinterpret_cast<bf16x8*>(sd.k1) = st.ks1;
;     else if constexpr (KS == 2) *reinterpret_cast<bf16x8*>(sd.v0) = st.vs0;
;     else *reinterpret_cast<bf16x8*>(sd.v1) = st.vs1;
;   }
;   SBAR();
;   o[2] = MFMA32(pa, PKV(cur.l2, cur.h2), o[2]); SBAR(); sm1_chunk<KS * 4 + 2>(p0, p1); SM2_UNIT(2 * KS); SBAR();
;   o[3] = MFMA32(pa, PKV(cur.l3, cur.h3), o[3]); SBAR(); sm1_chunk<KS * 4 + 3>(p0, p1); SBAR();
;   if constexpr (!SAFE) { lacc = MFMA32(pa, ones, lacc); SBAR(); }
; }
; template <bool SAFE> ...
;   bf16x8 kb[8];
; #pragma unroll
;   for (int d0 = 0; d0 < 4; ++d0) { const int cb = (cb0 + d0 * 16 + hi * 8) * 2;
;     kb[2 * d0] = *reinterpret_cast<const bf16x8*>((const char*)Ks + KSWZ(r32, cb));
;     kb[2 * d0 + 1] = *reinterpret_cast<const bf16x8*>((const char*)Ks + KSWZ(32 + r32, cb)); }
;   VFrag fa, fb;
;   vfrag_issue<0>(fa, vb);
;   p0 = MFMA32(kb[0], qr[0], cinit); p1 = MFMA32(kb[1], qr[0], cinit);
; #pragma unroll
;   for (int d0 = 1; d0 < 4; ++d0) { p0 = MFMA32(kb[2 * d0], qr[d0], p0); p1 = MFMA32(kb[2 * d0 + 1], qr[d0], p1); }
;   SBAR();
;   unsigned a0, a1, b0, b1; ps = 0.f;
;   fused_ks<0, SAFE>(o, lacc, vb, fa, fb, p0, p1, ps, a0, a1, b0, b1, pa0, pa1, pa2, pa3, st, sd, dow, ones);
;   fused_ks<1, SAFE>(o, lacc, vb, fb, fa, p0, p1, ps, a0, a1, b0, b1, pa0, pa1, pa2, pa3, st, sd, dow, ones);
;   fused_ks<2, SAFE>(o, lacc, vb, fa, fb, p0, p1, ps, a0, a1, b0, b1, pa0, pa1, pa2, pa3, st, sd, dow, ones);
;   fused_ks<3, SAFE>(o, lacc, vb, fb, fa, p0, p1, ps, a0, a1, b0, b1, pa0, pa1, pa2, pa3, st, sd, dow, ones);
.LBB0_105:
	ds_read_b128 v[212:215], v77 offset:49152
	ds_read_b128 v[216:219], v77 offset:57344
	s_lshl_b32 s7, s6, 14
	s_add_i32 s66, s7, 0
	s_add_i32 s98, s5, 2
	s_min_i32 s98, s98, s93
	s_mul_i32 s98, s98, 0x60000
	s_add_u32 s98, s10, s98
	s_addc_u32 s99, s11, 0
	s_add_u32 s100, s98, 0x30000
	s_addc_u32 s101, s99, 0
	v_add_u32_e32 v173, s66, v209
	v_mov_b32_e32 v176, v180
	v_mfma_f32_32x32x16_bf16 v[112:127], v[68:71], v[132:135], v[80:95]
	v_mov_b32_e32 v180, v160
	v_add_u32_e32 v160, s66, v210
	v_lshl_add_u32 v194, s4, 14, v211
	s_mov_b32 s8, s9
	s_lshl_b32 s9, s9, 14
	s_add_i32 s9, s9, 0
	v_add_u32_e32 v76, s9, v207
	v_mov_b32_e32 v184, v170
	v_mfma_f32_32x32x16_bf16 v[96:111], v[72:75], v[132:135], v[80:95]
	ds_read_b128 v[68:71], v173 offset:49152
	ds_read_b128 v[72:75], v173 offset:57344
	v_mov_b32_e32 v177, v181
	v_mov_b32_e32 v172, v188
	v_mov_b32_e32 v181, v161
	v_add_u32_e32 v188, s9, v205
	v_add_u32_e32 v161, s9, v203
	v_add_u32_e32 v170, s9, v204
	v_mfma_f32_16x16x32_bf16 v[64:67], v[180:183], v[148:151], v[64:67]
	s_waitcnt lgkmcnt(3)
	v_mfma_f32_32x32x16_bf16 v[112:127], v[212:215], v[136:139], v[112:127]
	ds_read_b128 v[212:215], v160 offset:49152
	s_waitcnt vmcnt(3)
	ds_write_b128 v161, v[166:169] offset:49152
	global_load_dwordx4 v[166:169], v247, s[98:99] offset:1024
	v_mov_b32_e32 v185, v171
	s_waitcnt lgkmcnt(4)
	v_mfma_f32_32x32x16_bf16 v[96:111], v[216:219], v[136:139], v[96:111]
	ds_read_b128 v[216:219], v160 offset:57344
	v_mov_b32_e32 v173, v189
	v_add_u32_e32 v189, s9, v206
	v_add_u32_e32 v77, s9, v208
	v_mfma_f32_16x16x32_bf16 v[64:67], v[184:187], v[148:151], v[64:67]
	s_waitcnt lgkmcnt(4)
	v_mfma_f32_32x32x16_bf16 v[112:127], v[68:71], v[140:143], v[112:127]
	ds_read_b64_tr_b16 v[220:221], v194 offset:0
	ds_read_b64_tr_b16 v[222:223], v194 offset:0x800
	s_waitcnt vmcnt(3)
	ds_write_b128 v170, v[162:165] offset:49152
	global_load_dwordx4 v[162:165], v247, s[100:101] offset:1024
	v_mfma_f32_16x16x32_bf16 v[64:67], v[176:179], v[148:151], v[64:67]
	s_waitcnt lgkmcnt(6)
	v_mfma_f32_32x32x16_bf16 v[96:111], v[72:75], v[140:143], v[96:111]
	v_mfma_f32_16x16x32_bf16 v[64:67], v[172:175], v[148:151], v[64:67]
	s_waitcnt lgkmcnt(5)
	v_mfma_f32_32x32x16_bf16 v[112:127], v[212:215], v[144:147], v[112:127]
	ds_read_b64_tr_b16 v[212:213], v194 offset:0x200
	ds_read_b64_tr_b16 v[214:215], v194 offset:0xa00
	ds_read_b64_tr_b16 v[224:225], v194 offset:0x400
	ds_read_b64_tr_b16 v[226:227], v194 offset:0xc00
	ds_read_b64_tr_b16 v[228:229], v194 offset:0x600
	ds_read_b64_tr_b16 v[230:231], v194 offset:0xe00
	s_waitcnt lgkmcnt(7)
	v_mfma_f32_32x32x16_bf16 v[96:111], v[216:219], v[144:147], v[96:111]
	ds_read_b64_tr_b16 v[216:217], v194 offset:0x1000
	ds_read_b64_tr_b16 v[218:219], v194 offset:0x1800
	ds_read_b64_tr_b16 v[232:233], v194 offset:0x1200
	ds_read_b64_tr_b16 v[234:235], v194 offset:0x1a00
	ds_read_b64_tr_b16 v[236:237], v194 offset:0x1400
	ds_read_b64_tr_b16 v[238:239], v194 offset:0x1c00
	ds_read_b64_tr_b16 v[240:241], v194 offset:0x1600
	ds_read_b64_tr_b16 v[242:243], v194 offset:0x1e00
	s_waitcnt lgkmcnt(8)
	v_mfma_f32_32x32x16_bf16 v[48:63], v[180:183], v[220:223], v[48:63]
	s_nop 0
	v_exp_f32_e32 v112, v112
	v_exp_f32_e32 v113, v113
	v_mfma_f32_32x32x16_bf16 v[32:47], v[180:183], v[212:215], v[32:47]
	v_exp_f32_e32 v114, v114
	v_exp_f32_e32 v115, v115
	v_mfma_f32_32x32x16_bf16 v[0:15], v[180:183], v[224:227], v[0:15]
	v_exp_f32_e32 v171, v116
	v_cvt_pk_bf16_f32 v160, v112, v113
	v_cvt_pk_bf16_f32 v161, v114, v115
	v_exp_f32_e32 v220, v117
	v_mfma_f32_32x32x16_bf16 v[16:31], v[180:183], v[228:231], v[16:31]
	v_exp_f32_e32 v221, v118
	v_exp_f32_e32 v222, v119
	ds_read_b64_tr_b16 v[112:113], v194 offset:0x2000
	ds_read_b64_tr_b16 v[114:115], v194 offset:0x2800
	ds_read_b64_tr_b16 v[116:117], v194 offset:0x2200
	ds_read_b64_tr_b16 v[118:119], v194 offset:0x2a00
	ds_read_b64_tr_b16 v[248:249], v194 offset:0x2400
	ds_read_b64_tr_b16 v[250:251], v194 offset:0x2c00
	ds_read_b64_tr_b16 v[212:213], v194 offset:0x2600
	ds_read_b64_tr_b16 v[214:215], v194 offset:0x2e00
	s_waitcnt lgkmcnt(8)
	v_mfma_f32_32x32x16_bf16 v[48:63], v[184:187], v[216:219], v[48:63]
	v_cvt_pk_bf16_f32 v182, v171, v220
	v_cvt_pk_bf16_f32 v183, v221, v222
	v_exp_f32_e32 v120, v120
	v_exp_f32_e32 v121, v121
	v_mfma_f32_32x32x16_bf16 v[32:47], v[184:187], v[232:235], v[32:47]
	v_exp_f32_e32 v122, v122
	v_exp_f32_e32 v123, v123
	v_mfma_f32_32x32x16_bf16 v[0:15], v[184:187], v[236:239], v[0:15]
	v_exp_f32_e32 v180, v124
	v_exp_f32_e32 v181, v125
	v_cvt_pk_bf16_f32 v170, v120, v121
	v_cvt_pk_bf16_f32 v171, v122, v123
	v_mfma_f32_32x32x16_bf16 v[16:31], v[184:187], v[240:243], v[16:31]
	v_exp_f32_e32 v220, v126
	v_exp_f32_e32 v221, v127
	s_waitcnt lgkmcnt(0)
	s_barrier
; #define SBAR() __builtin_amdgcn_sched_barrier(0)
; template <int KS, bool SAFE> __device__ __forceinline__ void fused_ks(f32x16* o, f32x16& lacc, int vb, const VFrag& cur, VFrag& nxt, f32x16& p0, f32x16& p1, float& ps, ...
;   if constexpr (KS < 3) { vfrag_issue<KS + 1>(nxt, vb); asm volatile("s_waitcnt lgkmcnt(8)" ::: "memory"); }
;   else asm volatile("s_waitcnt lgkmcnt(0)" ::: "memory");
;   const bf16x8 pa = (KS == 0) ? pa0 : (KS == 1) ? pa1 : (KS == 2) ? pa2 : pa3;
;   SBAR();
;   o[0] = MFMA32(pa, PKV(cur.l0, cur.h0), o[0]); SBAR(); sm1_chunk<KS * 4 + 0>(p0, p1); if constexpr (KS > 0) SM2_UNIT(2 * KS - 1); SBAR();
;   o[1] = MFMA32(pa, PKV(cur.l1, cur.h1), o[1]); SBAR(); sm1_chunk<KS * 4 + 1>(p0, p1);
;   if (dow) {
;     if constexpr (KS == 0) { asm volatile("s_waitcnt vmcnt(0)" ::: "memory"); *reinterpret_cast<bf16x8*>(sd.k0) = st.ks0; }
;     else if constexpr (KS == 1) *reinterpret_cast<bf16x8*>(sd.k1) = st.ks1;
;     else if constexpr (KS == 2) *reinterpret_cast<bf16x8*>(sd.v0) = st.vs0;
;     else *reinterpret_cast<bf16x8*>(sd.v1) = st.vs1;
;   }
;   SBAR();
;   o[2] = MFMA32(pa, PKV(cur.l2, cur.h2), o[2]); SBAR(); sm1_chunk<KS * 4 + 2>(p0, p1); SM2_UNIT(2 * KS); SBAR();
;   o[3] = MFMA32(pa, PKV(cur.l3, cur.h3), o[3]); SBAR(); sm1_chunk<KS * 4 + 3>(p0, p1); SBAR();
;   if constexpr (!SAFE) { lacc = MFMA32(pa, ones, lacc); SBAR(); }
; }
; template <bool SAFE>
; __device__ __forceinline__ void diff_core(const bf16* __restrict__ Kh, const bf16* __restrict__ Vh, const int NT, const bf16x8* qr, char* lds,
;                                           const int wid, const int lane_unused, f32x16* o, f32x16& lacc, float& l_reg) {
;     ...
;   for (int j = 1; j < NT; ++j) {
;     const bool dow = true;
;     const bf16* Kc = (const bf16*)((const char*)K_lds + bc * SHM_K);
;     StgDst sd;
;     sd.v0 = (char*)V_lds + bn * SHM_V + vst0; sd.v1 = (char*)V_lds + bn * SHM_V + vst1;
;     sd.k0 = (char*)K_lds + bn * SHM_K + kw0;  sd.k1 = (char*)K_lds + bn * SHM_K + kw1;
;     tile_step<SAFE>(o, lacc, Kc, vb0 + bp * SHM_V, qr, rk, hi, cb0, p0, p1, cinit, ps, pa0, pa1, pa2, pa3, sr_[0], sd, dow, ones);
;     SLOAD(0, min(j + 2, NT - 1) * 64);
;     SBAR();
;     if constexpr (SAFE) FIXUP(Kc, false);
;     asm volatile("s_waitcnt lgkmcnt(0)" ::: "memory"); __builtin_amdgcn_s_barrier(); asm volatile("" ::: "memory");
;     const int t_ = bp; bp = bc; bc = bn; bn = t_;
	v_mfma_f32_32x32x16_bf16 v[48:63], v[176:179], v[112:115], v[48:63]
	ds_read_b128 v[68:71], v76 offset:49152
	ds_read_b128 v[72:75], v76 offset:57344
	ds_read_b64_tr_b16 v[120:121], v194 offset:0x3000
	ds_read_b64_tr_b16 v[122:123], v194 offset:0x3800
	ds_read_b64_tr_b16 v[124:125], v194 offset:0x3200
	ds_read_b64_tr_b16 v[126:127], v194 offset:0x3a00
	ds_read_b64_tr_b16 v[252:253], v194 offset:0x3400
	ds_read_b64_tr_b16 v[254:255], v194 offset:0x3c00
	ds_read_b64_tr_b16 v[216:217], v194 offset:0x3600
	ds_read_b64_tr_b16 v[218:219], v194 offset:0x3e00
	v_cvt_pk_bf16_f32 v186, v180, v181
	v_cvt_pk_bf16_f32 v187, v220, v221
	v_exp_f32_e32 v96, v96
	v_exp_f32_e32 v97, v97
	v_mfma_f32_32x32x16_bf16 v[32:47], v[176:179], v[116:119], v[32:47]
	v_exp_f32_e32 v98, v98
	v_exp_f32_e32 v99, v99
	s_waitcnt vmcnt(3)
	ds_write_b128 v188, v[156:159]
	global_load_dwordx4 v[156:159], v247, s[98:99] offset:2048
	v_mfma_f32_32x32x16_bf16 v[0:15], v[176:179], v[248:251], v[0:15]
	v_cvt_pk_bf16_f32 v180, v96, v97
	v_cvt_pk_bf16_f32 v181, v98, v99
	v_exp_f32_e32 v100, v100
	v_exp_f32_e32 v101, v101
	v_mfma_f32_32x32x16_bf16 v[16:31], v[176:179], v[212:215], v[16:31]
	v_exp_f32_e32 v96, v102
	v_exp_f32_e32 v97, v103
	s_waitcnt lgkmcnt(0)
	v_mfma_f32_32x32x16_bf16 v[48:63], v[172:175], v[120:123], v[48:63]
	v_cvt_pk_bf16_f32 v178, v100, v101
	v_cvt_pk_bf16_f32 v179, v96, v97
	v_exp_f32_e32 v98, v104
	v_exp_f32_e32 v99, v105
	v_mfma_f32_32x32x16_bf16 v[32:47], v[172:175], v[124:127], v[32:47]
	v_exp_f32_e32 v96, v106
	v_exp_f32_e32 v97, v107
	s_waitcnt vmcnt(3)
	ds_write_b128 v189, v[152:155]
	global_load_dwordx4 v[152:155], v247, s[100:101] offset:2048
	v_mfma_f32_32x32x16_bf16 v[0:15], v[172:175], v[252:255], v[0:15]
	v_cvt_pk_bf16_f32 v188, v98, v99
	v_cvt_pk_bf16_f32 v189, v96, v97
	v_exp_f32_e32 v100, v108
	v_exp_f32_e32 v101, v109
	v_mfma_f32_32x32x16_bf16 v[16:31], v[172:175], v[216:219], v[16:31]
	v_exp_f32_e32 v96, v110
	v_exp_f32_e32 v97, v111
	v_cvt_pk_bf16_f32 v174, v100, v101
	v_cvt_pk_bf16_f32 v175, v96, v97
	s_add_i32 s5, s5, 1
	s_mov_b32 s9, s4
	s_mov_b32 s4, s6
	s_cmp_lg_u32 s92, s5
	s_mov_b32 s6, s8
	s_cbranch_scc1 .LBB0_105
; #define MFMA32(a, b, c) __builtin_amdgcn_mfma_f32_32x32x16_bf16(a, b, c, 0, 0, 0)
; template <bool SAFE>
; __device__ __forceinline__ void diff_core(const bf16* __restrict__ Kh, const bf16* __restrict__ Vh, const int NT, const bf16x8* qr, char* lds,
;                                           const int wid, const int lane_unused, f32x16* o, f32x16& lacc, float& l_reg) {
;     ...
;   pv_d0(o, vb0 + bp * SHM_V, pa0, pa1, pa2, pa3);
;   if constexpr (!SAFE) {
;     lacc = MFMA32(pa0, ones, lacc); lacc = MFMA32(pa1, ones, lacc); lacc = MFMA32(pa2, ones, lacc); lacc = MFMA32(pa3, ones, lacc); }
; __device__ __forceinline__ void diff_attn_item(const bf16* __restrict__ qkv, bf16* __restrict__ mix, const float* __restrict__ dg,
;                                int tok0  , int key0  , int seq, int head, float lam, float oscale, const int W) {
;     ...
;     bool bad = (FORCE_SAFE != 0);
; #pragma unroll
;     for (int r = 0; r < 16; ++r) bad = bad || !(lacc[r] < 1.0e30f);
;     if (lane == 0) flag_l[wid] = __any(bad) ? 1 : 0;
	s_waitcnt vmcnt(0)
	v_add_u32_e32 v168, s7, v211
	ds_read_b64_tr_b16 v[80:81], v168 offset:0
	ds_read_b64_tr_b16 v[82:83], v168 offset:0x800
	ds_read_b64_tr_b16 v[84:85], v168 offset:0x1000
	ds_read_b64_tr_b16 v[86:87], v168 offset:0x1800
	ds_read_b64_tr_b16 v[88:89], v168 offset:0x2000
	ds_read_b64_tr_b16 v[90:91], v168 offset:0x2800
	ds_read_b64_tr_b16 v[92:93], v168 offset:0x3000
	ds_read_b64_tr_b16 v[94:95], v168 offset:0x3800
	s_waitcnt lgkmcnt(0)
	s_waitcnt vmcnt(0)
	v_mov_b32_e32 v162, v182
	v_mov_b32_e32 v163, v183
	v_mov_b32_e32 v172, v186
	v_mov_b32_e32 v173, v187
	v_mov_b32_e32 v182, v178
	v_mov_b32_e32 v183, v179
	v_mov_b32_e32 v190, v174
	v_mov_b32_e32 v191, v175
	ds_read_b64_tr_b16 v[96:97], v168 offset:0x200
	ds_read_b64_tr_b16 v[98:99], v168 offset:0xa00
	ds_read_b64_tr_b16 v[100:101], v168 offset:0x1200
	ds_read_b64_tr_b16 v[102:103], v168 offset:0x1a00
	ds_read_b64_tr_b16 v[104:105], v168 offset:0x2200
	ds_read_b64_tr_b16 v[106:107], v168 offset:0x2a00
	ds_read_b64_tr_b16 v[108:109], v168 offset:0x3200
	ds_read_b64_tr_b16 v[110:111], v168 offset:0x3a00
	s_waitcnt lgkmcnt(0)
	ds_read_b64_tr_b16 v[112:113], v168 offset:0x400
	ds_read_b64_tr_b16 v[114:115], v168 offset:0xc00
	ds_read_b64_tr_b16 v[116:117], v168 offset:0x1400
	ds_read_b64_tr_b16 v[118:119], v168 offset:0x1c00
	ds_read_b64_tr_b16 v[120:121], v168 offset:0x2400
	ds_read_b64_tr_b16 v[122:123], v168 offset:0x2c00
	ds_read_b64_tr_b16 v[124:125], v168 offset:0x3400
	ds_read_b64_tr_b16 v[126:127], v168 offset:0x3c00
	s_waitcnt lgkmcnt(0)
	ds_read_b64_tr_b16 v[152:153], v168 offset:0x600
	ds_read_b64_tr_b16 v[154:155], v168 offset:0xe00
	ds_read_b64_tr_b16 v[156:157], v168 offset:0x1600
	ds_read_b64_tr_b16 v[158:159], v168 offset:0x1e00
	ds_read_b64_tr_b16 v[164:165], v168 offset:0x2600
	ds_read_b64_tr_b16 v[166:167], v168 offset:0x2e00
	ds_read_b64_tr_b16 v[174:175], v168 offset:0x3600
	ds_read_b64_tr_b16 v[176:177], v168 offset:0x3e00
	s_waitcnt lgkmcnt(0)
	v_mfma_f32_16x16x32_bf16 v[64:67], v[160:163], v[148:151], v[64:67]
	v_cmp_eq_u32_e32 vcc, 0, v200
	v_mfma_f32_32x32x16_bf16 v[48:63], v[160:163], v[80:83], v[48:63]
	v_mfma_f32_32x32x16_bf16 v[32:47], v[160:163], v[96:99], v[32:47]
	v_mfma_f32_32x32x16_bf16 v[0:15], v[160:163], v[112:115], v[0:15]
	v_mfma_f32_32x32x16_bf16 v[16:31], v[160:163], v[152:155], v[16:31]
	v_mfma_f32_16x16x32_bf16 v[64:67], v[170:173], v[148:151], v[64:67]
	v_mfma_f32_32x32x16_bf16 v[48:63], v[170:173], v[84:87], v[48:63]
	v_mfma_f32_32x32x16_bf16 v[32:47], v[170:173], v[100:103], v[32:47]
	v_mfma_f32_32x32x16_bf16 v[0:15], v[170:173], v[116:119], v[0:15]
	v_mfma_f32_32x32x16_bf16 v[16:31], v[170:173], v[156:159], v[16:31]
	v_mfma_f32_16x16x32_bf16 v[64:67], v[180:183], v[148:151], v[64:67]
	v_mfma_f32_32x32x16_bf16 v[48:63], v[180:183], v[88:91], v[48:63]
	v_mfma_f32_32x32x16_bf16 v[32:47], v[180:183], v[104:107], v[32:47]
	v_mfma_f32_32x32x16_bf16 v[0:15], v[180:183], v[120:123], v[0:15]
	v_mfma_f32_32x32x16_bf16 v[16:31], v[180:183], v[164:167], v[16:31]
	v_mfma_f32_16x16x32_bf16 v[64:67], v[188:191], v[148:151], v[64:67]
	v_mfma_f32_32x32x16_bf16 v[48:63], v[188:191], v[92:95], v[48:63]
	v_mfma_f32_32x32x16_bf16 v[32:47], v[188:191], v[108:111], v[32:47]
	v_mfma_f32_32x32x16_bf16 v[0:15], v[188:191], v[124:127], v[0:15]
	v_mfma_f32_32x32x16_bf16 v[16:31], v[188:191], v[174:177], v[16:31]
	v_and_b32_e32 v248, 15, v200
	v_lshrrev_b32_e32 v249, 4, v200
	v_and_b32_e32 v250, 1, v200
	v_lshlrev_b32_e32 v249, 4, v249
	v_lshl_add_u32 v249, v250, 6, v249
	v_add_u32_e32 v249, s62, v249
	v_cmp_gt_u32_e64 s[98:99], 2, v248
	v_lshl_add_u32 v250, v198, 4, s62
	s_nop 7
	s_and_saveexec_b64 s[100:101], s[98:99]
	ds_write_b128 v249, v[64:67]
	s_mov_b64 exec, s[100:101]
	s_waitcnt lgkmcnt(0)
	ds_read_b128 v[64:67], v250
	ds_read_b128 v[68:71], v250 offset:32
	ds_read_b128 v[72:75], v250 offset:64
	ds_read_b128 v[76:79], v250 offset:96
	s_waitcnt lgkmcnt(0)
	s_and_saveexec_b64 s[6:7], vcc
	s_cbranch_execz .LBB0_108
	s_nop 5
	v_cmp_ngt_f32_e32 vcc, s85, v64
	v_cmp_ngt_f32_e64 s[4:5], s85, v65
	s_or_b64 s[4:5], vcc, s[4:5]
	v_cmp_ngt_f32_e32 vcc, s85, v66
	s_or_b64 s[4:5], s[4:5], vcc
	v_cmp_ngt_f32_e32 vcc, s85, v67
	s_or_b64 s[4:5], s[4:5], vcc
	v_cmp_ngt_f32_e32 vcc, s85, v68
	s_or_b64 s[4:5], s[4:5], vcc
	v_cmp_ngt_f32_e32 vcc, s85, v69
	s_or_b64 s[4:5], s[4:5], vcc
	v_cmp_ngt_f32_e32 vcc, s85, v70
	s_or_b64 s[4:5], s[4:5], vcc
	v_cmp_ngt_f32_e32 vcc, s85, v71
	s_or_b64 s[4:5], s[4:5], vcc
	v_cmp_ngt_f32_e32 vcc, s85, v72
	s_or_b64 s[4:5], s[4:5], vcc
	v_cmp_ngt_f32_e32 vcc, s85, v73
	s_or_b64 s[4:5], s[4:5], vcc
	v_cmp_ngt_f32_e32 vcc, s85, v74
	s_or_b64 s[4:5], s[4:5], vcc
	v_cmp_ngt_f32_e32 vcc, s85, v75
	s_or_b64 s[4:5], s[4:5], vcc
	v_cmp_ngt_f32_e32 vcc, s85, v76
	s_or_b64 s[4:5], s[4:5], vcc
	v_cmp_ngt_f32_e32 vcc, s85, v77
	s_or_b64 s[4:5], s[4:5], vcc
	v_cmp_ngt_f32_e32 vcc, s85, v78
	s_or_b64 s[4:5], s[4:5], vcc
	v_cmp_ngt_f32_e32 vcc, s85, v79
	s_or_b64 s[4:5], s[4:5], vcc
	v_cndmask_b32_e64 v80, 0, 1, s[4:5]
	v_cmp_ne_u32_e32 vcc, 0, v80
	s_cmp_lg_u64 vcc, 0
	s_cselect_b64 s[4:5], -1, 0
	v_cndmask_b32_e64 v80, 0, 1, s[4:5]
	v_readlane_b32 s4, v246, 17
	s_nop 1
	v_mov_b32_e32 v81, s4
	ds_write_b32 v81, v80

; template <int KS, bool SAFE> __device__ __forceinline__ void fused_ks(f32x16* o, f32x16& lacc, int vb, const VFrag& cur, VFrag& nxt, f32x16& p0, f32x16& p1, float& ps, ...
;   if constexpr (KS < 3) { vfrag_issue<KS + 1>(nxt, vb); asm volatile("s_waitcnt lgkmcnt(8)" ::: "memory"); }
;   else asm volatile("s_waitcnt lgkmcnt(0)" ::: "memory");
;   const bf16x8 pa = (KS == 0) ? pa0 : (KS == 1) ? pa1 : (KS == 2) ? pa2 : pa3;
;   SBAR();
;   o[0] = MFMA32(pa, PKV(cur.l0, cur.h0), o[0]); SBAR(); sm1_chunk<KS * 4 + 0>(p0, p1); if constexpr (KS > 0) SM2_UNIT(2 * KS - 1); SBAR();
;   o[1] = MFMA32(pa, PKV(cur.l1, cur.h1), o[1]); SBAR(); sm1_chunk<KS * 4 + 1>(p0, p1);
;   if (dow) {
;     if constexpr (KS == 0) { asm volatile("s_waitcnt vmcnt(0)" ::: "memory"); *reinterpret_cast<bf16x8*>(sd.k0) = st.ks0; }
;     else if constexpr (KS == 1) *reinterpret_cast<bf16x8*>(sd.k1) = st.ks1;
;     else if constexpr (KS == 2) *reinterpret_cast<bf16x8*>(sd.v0) = st.vs0;
;     else *reinterpret_cast<bf16x8*>(sd.v1) = st.vs1;
;   }
;   SBAR();
;   o[2] = MFMA32(pa, PKV(cur.l2, cur.h2), o[2]); SBAR(); sm1_chunk<KS * 4 + 2>(p0, p1); SM2_UNIT(2 * KS); SBAR();
;   o[3] = MFMA32(pa, PKV(cur.l3, cur.h3), o[3]); SBAR(); sm1_chunk<KS * 4 + 3>(p0, p1); SBAR();
;   if constexpr (!SAFE) { lacc = MFMA32(pa, ones, lacc); SBAR(); }
; }
; template <bool SAFE> ...
;   bf16x8 kb[8];
; #pragma unroll
;   for (int d0 = 0; d0 < 4; ++d0) { const int cb = (cb0 + d0 * 16 + hi * 8) * 2;
;     kb[2 * d0] = *reinterpret_cast<const bf16x8*>((const char*)Ks + KSWZ(r32, cb));
;     kb[2 * d0 + 1] = *reinterpret_cast<const bf16x8*>((const char*)Ks + KSWZ(32 + r32, cb)); }
;   VFrag fa, fb;
;   vfrag_issue<0>(fa, vb);
;   p0 = MFMA32(kb[0], qr[0], cinit); p1 = MFMA32(kb[1], qr[0], cinit);
; #pragma unroll
;   for (int d0 = 1; d0 < 4; ++d0) { p0 = MFMA32(kb[2 * d0], qr[d0], p0); p1 = MFMA32(kb[2 * d0 + 1], qr[d0], p1); }
;   SBAR();
;   unsigned a0, a1, b0, b1; ps = 0.f;
;   fused_ks<0, SAFE>(o, lacc, vb, fa, fb, p0, p1, ps, a0, a1, b0, b1, pa0, pa1, pa2, pa3, st, sd, dow, ones);
;   fused_ks<1, SAFE>(o, lacc, vb, fb, fa, p0, p1, ps, a0, a1, b0, b1, pa0, pa1, pa2, pa3, st, sd, dow, ones);
;   fused_ks<2, SAFE>(o, lacc, vb, fa, fb, p0, p1, ps, a0, a1, b0, b1, pa0, pa1, pa2, pa3, st, sd, dow, ones);
;   fused_ks<3, SAFE>(o, lacc, vb, fb, fa, p0, p1, ps, a0, a1, b0, b1, pa0, pa1, pa2, pa3, st, sd, dow, ones);
.LBB0_316:
	ds_read_b128 v[212:215], v77 offset:49152
	ds_read_b128 v[216:219], v77 offset:57344
	s_lshl_b32 s11, s10, 14
	s_add_i32 s8, s11, 0
	s_add_i32 s98, s7, 2
	s_min_i32 s98, s98, s64
	s_mul_i32 s98, s98, 0x60000
	s_add_u32 s98, s14, s98
	s_addc_u32 s99, s15, 0
	s_add_u32 s100, s98, 0x30000
	s_addc_u32 s101, s99, 0
	v_add_u32_e32 v173, s8, v209
	v_mov_b32_e32 v176, v180
	v_mfma_f32_32x32x16_bf16 v[112:127], v[68:71], v[132:135], v[80:95]
	v_mov_b32_e32 v180, v160
	v_add_u32_e32 v160, s8, v210
	v_lshl_add_u32 v194, s6, 14, v211
	s_lshl_b32 s9, s27, 14
	s_add_i32 s9, s9, 0
	s_mov_b32 s26, s27
	v_add_u32_e32 v76, s9, v207
	v_mov_b32_e32 v184, v170
	v_mfma_f32_32x32x16_bf16 v[96:111], v[72:75], v[132:135], v[80:95]
	ds_read_b128 v[68:71], v173 offset:49152
	ds_read_b128 v[72:75], v173 offset:57344
	v_mov_b32_e32 v177, v181
	v_mov_b32_e32 v172, v188
	v_mov_b32_e32 v181, v161
	v_add_u32_e32 v188, s9, v205
	v_add_u32_e32 v161, s9, v203
	v_add_u32_e32 v170, s9, v204
	v_mfma_f32_16x16x32_bf16 v[64:67], v[180:183], v[148:151], v[64:67]
	s_waitcnt lgkmcnt(3)
	v_mfma_f32_32x32x16_bf16 v[112:127], v[212:215], v[136:139], v[112:127]
	ds_read_b128 v[212:215], v160 offset:49152
	s_waitcnt vmcnt(3)
	ds_write_b128 v161, v[166:169] offset:49152
	global_load_dwordx4 v[166:169], v247, s[98:99] offset:1024
	v_mov_b32_e32 v185, v171
	s_waitcnt lgkmcnt(4)
	v_mfma_f32_32x32x16_bf16 v[96:111], v[216:219], v[136:139], v[96:111]
	ds_read_b128 v[216:219], v160 offset:57344
	v_mov_b32_e32 v173, v189
	v_add_u32_e32 v189, s9, v206
	v_add_u32_e32 v77, s9, v208
	v_mfma_f32_16x16x32_bf16 v[64:67], v[184:187], v[148:151], v[64:67]
	s_waitcnt lgkmcnt(4)
	v_mfma_f32_32x32x16_bf16 v[112:127], v[68:71], v[140:143], v[112:127]
	ds_read_b64_tr_b16 v[220:221], v194 offset:0
	ds_read_b64_tr_b16 v[222:223], v194 offset:0x800
	s_waitcnt vmcnt(3)
	ds_write_b128 v170, v[162:165] offset:49152
	global_load_dwordx4 v[162:165], v247, s[100:101] offset:1024
	v_mfma_f32_16x16x32_bf16 v[64:67], v[176:179], v[148:151], v[64:67]
	s_waitcnt lgkmcnt(6)
	v_mfma_f32_32x32x16_bf16 v[96:111], v[72:75], v[140:143], v[96:111]
	v_mfma_f32_16x16x32_bf16 v[64:67], v[172:175], v[148:151], v[64:67]
	s_waitcnt lgkmcnt(5)
	v_mfma_f32_32x32x16_bf16 v[112:127], v[212:215], v[144:147], v[112:127]
	ds_read_b64_tr_b16 v[212:213], v194 offset:0x200
	ds_read_b64_tr_b16 v[214:215], v194 offset:0xa00
	ds_read_b64_tr_b16 v[224:225], v194 offset:0x400
	ds_read_b64_tr_b16 v[226:227], v194 offset:0xc00
	ds_read_b64_tr_b16 v[228:229], v194 offset:0x600
	ds_read_b64_tr_b16 v[230:231], v194 offset:0xe00
	s_waitcnt lgkmcnt(7)
	v_mfma_f32_32x32x16_bf16 v[96:111], v[216:219], v[144:147], v[96:111]
	ds_read_b64_tr_b16 v[216:217], v194 offset:0x1000
	ds_read_b64_tr_b16 v[218:219], v194 offset:0x1800
	ds_read_b64_tr_b16 v[232:233], v194 offset:0x1200
	ds_read_b64_tr_b16 v[234:235], v194 offset:0x1a00
	ds_read_b64_tr_b16 v[236:237], v194 offset:0x1400
	ds_read_b64_tr_b16 v[238:239], v194 offset:0x1c00
	ds_read_b64_tr_b16 v[240:241], v194 offset:0x1600
	ds_read_b64_tr_b16 v[242:243], v194 offset:0x1e00
	s_waitcnt lgkmcnt(8)
	v_mfma_f32_32x32x16_bf16 v[48:63], v[180:183], v[220:223], v[48:63]
	s_nop 0
	v_exp_f32_e32 v112, v112
	v_exp_f32_e32 v113, v113
	v_mfma_f32_32x32x16_bf16 v[32:47], v[180:183], v[212:215], v[32:47]
	v_exp_f32_e32 v114, v114
	v_exp_f32_e32 v115, v115
	v_mfma_f32_32x32x16_bf16 v[0:15], v[180:183], v[224:227], v[0:15]
	v_exp_f32_e32 v171, v116
	v_cvt_pk_bf16_f32 v160, v112, v113
	v_cvt_pk_bf16_f32 v161, v114, v115
	v_exp_f32_e32 v220, v117
	v_mfma_f32_32x32x16_bf16 v[16:31], v[180:183], v[228:231], v[16:31]
	v_exp_f32_e32 v221, v118
	v_exp_f32_e32 v222, v119
	ds_read_b64_tr_b16 v[112:113], v194 offset:0x2000
	ds_read_b64_tr_b16 v[114:115], v194 offset:0x2800
	ds_read_b64_tr_b16 v[116:117], v194 offset:0x2200
	ds_read_b64_tr_b16 v[118:119], v194 offset:0x2a00
	ds_read_b64_tr_b16 v[248:249], v194 offset:0x2400
	ds_read_b64_tr_b16 v[250:251], v194 offset:0x2c00
	ds_read_b64_tr_b16 v[212:213], v194 offset:0x2600
	ds_read_b64_tr_b16 v[214:215], v194 offset:0x2e00
	s_waitcnt lgkmcnt(8)
	v_mfma_f32_32x32x16_bf16 v[48:63], v[184:187], v[216:219], v[48:63]
	v_cvt_pk_bf16_f32 v182, v171, v220
	v_cvt_pk_bf16_f32 v183, v221, v222
	v_exp_f32_e32 v120, v120
	v_exp_f32_e32 v121, v121
	v_mfma_f32_32x32x16_bf16 v[32:47], v[184:187], v[232:235], v[32:47]
	v_exp_f32_e32 v122, v122
	v_exp_f32_e32 v123, v123
	v_mfma_f32_32x32x16_bf16 v[0:15], v[184:187], v[236:239], v[0:15]
	v_exp_f32_e32 v180, v124
	v_exp_f32_e32 v181, v125
	v_cvt_pk_bf16_f32 v170, v120, v121
	v_cvt_pk_bf16_f32 v171, v122, v123
	v_mfma_f32_32x32x16_bf16 v[16:31], v[184:187], v[240:243], v[16:31]
	v_exp_f32_e32 v220, v126
	v_exp_f32_e32 v221, v127
	s_waitcnt lgkmcnt(0)
	s_barrier
; #define SBAR() __builtin_amdgcn_sched_barrier(0)
; template <int KS, bool SAFE> __device__ __forceinline__ void fused_ks(f32x16* o, f32x16& lacc, int vb, const VFrag& cur, VFrag& nxt, f32x16& p0, f32x16& p1, float& ps, ...
;   if constexpr (KS < 3) { vfrag_issue<KS + 1>(nxt, vb); asm volatile("s_waitcnt lgkmcnt(8)" ::: "memory"); }
;   else asm volatile("s_waitcnt lgkmcnt(0)" ::: "memory");
;   const bf16x8 pa = (KS == 0) ? pa0 : (KS == 1) ? pa1 : (KS == 2) ? pa2 : pa3;
;   SBAR();
;   o[0] = MFMA32(pa, PKV(cur.l0, cur.h0), o[0]); SBAR(); sm1_chunk<KS * 4 + 0>(p0, p1); if constexpr (KS > 0) SM2_UNIT(2 * KS - 1); SBAR();
;   o[1] = MFMA32(pa, PKV(cur.l1, cur.h1), o[1]); SBAR(); sm1_chunk<KS * 4 + 1>(p0, p1);
;   if (dow) {
;     if constexpr (KS == 0) { asm volatile("s_waitcnt vmcnt(0)" ::: "memory"); *reinterpret_cast<bf16x8*>(sd.k0) = st.ks0; }
;     else if constexpr (KS == 1) *reinterpret_cast<bf16x8*>(sd.k1) = st.ks1;
;     else if constexpr (KS == 2) *reinterpret_cast<bf16x8*>(sd.v0) = st.vs0;
;     else *reinterpret_cast<bf16x8*>(sd.v1) = st.vs1;
;   }
;   SBAR();
;   o[2] = MFMA32(pa, PKV(cur.l2, cur.h2), o[2]); SBAR(); sm1_chunk<KS * 4 + 2>(p0, p1); SM2_UNIT(2 * KS); SBAR();
;   o[3] = MFMA32(pa, PKV(cur.l3, cur.h3), o[3]); SBAR(); sm1_chunk<KS * 4 + 3>(p0, p1); SBAR();
;   if constexpr (!SAFE) { lacc = MFMA32(pa, ones, lacc); SBAR(); }
; }
; template <bool SAFE>
; __device__ __forceinline__ void diff_core(const bf16* __restrict__ Kh, const bf16* __restrict__ Vh, const int NT, const bf16x8* qr, char* lds,
;                                           const int wid, const int lane_unused, f32x16* o, f32x16& lacc, float& l_reg) {
;     ...
;   for (int j = 1; j < NT; ++j) {
;     const bool dow = true;
;     const bf16* Kc = (const bf16*)((const char*)K_lds + bc * SHM_K);
;     StgDst sd;
;     sd.v0 = (char*)V_lds + bn * SHM_V + vst0; sd.v1 = (char*)V_lds + bn * SHM_V + vst1;
;     sd.k0 = (char*)K_lds + bn * SHM_K + kw0;  sd.k1 = (char*)K_lds + bn * SHM_K + kw1;
;     tile_step<SAFE>(o, lacc, Kc, vb0 + bp * SHM_V, qr, rk, hi, cb0, p0, p1, cinit, ps, pa0, pa1, pa2, pa3, sr_[0], sd, dow, ones);
;     SLOAD(0, min(j + 2, NT - 1) * 64);
;     SBAR();
;     if constexpr (SAFE) FIXUP(Kc, false);
;     asm volatile("s_waitcnt lgkmcnt(0)" ::: "memory"); __builtin_amdgcn_s_barrier(); asm volatile("" ::: "memory");
;     const int t_ = bp; bp = bc; bc = bn; bn = t_;
	v_mfma_f32_32x32x16_bf16 v[48:63], v[176:179], v[112:115], v[48:63]
	ds_read_b128 v[68:71], v76 offset:49152
	ds_read_b128 v[72:75], v76 offset:57344
	ds_read_b64_tr_b16 v[120:121], v194 offset:0x3000
	ds_read_b64_tr_b16 v[122:123], v194 offset:0x3800
	ds_read_b64_tr_b16 v[124:125], v194 offset:0x3200
	ds_read_b64_tr_b16 v[126:127], v194 offset:0x3a00
	ds_read_b64_tr_b16 v[252:253], v194 offset:0x3400
	ds_read_b64_tr_b16 v[254:255], v194 offset:0x3c00
	ds_read_b64_tr_b16 v[216:217], v194 offset:0x3600
	ds_read_b64_tr_b16 v[218:219], v194 offset:0x3e00
	v_cvt_pk_bf16_f32 v186, v180, v181
	v_cvt_pk_bf16_f32 v187, v220, v221
	v_exp_f32_e32 v96, v96
	v_exp_f32_e32 v97, v97
	v_mfma_f32_32x32x16_bf16 v[32:47], v[176:179], v[116:119], v[32:47]
	v_exp_f32_e32 v98, v98
	v_exp_f32_e32 v99, v99
	s_waitcnt vmcnt(3)
	ds_write_b128 v188, v[156:159]
	global_load_dwordx4 v[156:159], v247, s[98:99] offset:2048
	v_mfma_f32_32x32x16_bf16 v[0:15], v[176:179], v[248:251], v[0:15]
	v_cvt_pk_bf16_f32 v180, v96, v97
	v_cvt_pk_bf16_f32 v181, v98, v99
	v_exp_f32_e32 v100, v100
	v_exp_f32_e32 v101, v101
	v_mfma_f32_32x32x16_bf16 v[16:31], v[176:179], v[212:215], v[16:31]
	v_exp_f32_e32 v96, v102
	v_exp_f32_e32 v97, v103
	s_waitcnt lgkmcnt(0)
	v_mfma_f32_32x32x16_bf16 v[48:63], v[172:175], v[120:123], v[48:63]
	v_cvt_pk_bf16_f32 v178, v100, v101
	v_cvt_pk_bf16_f32 v179, v96, v97
	v_exp_f32_e32 v98, v104
	v_exp_f32_e32 v99, v105
	v_mfma_f32_32x32x16_bf16 v[32:47], v[172:175], v[124:127], v[32:47]
	v_exp_f32_e32 v96, v106
	v_exp_f32_e32 v97, v107
	s_waitcnt vmcnt(3)
	ds_write_b128 v189, v[152:155]
	global_load_dwordx4 v[152:155], v247, s[100:101] offset:2048
	v_mfma_f32_32x32x16_bf16 v[0:15], v[172:175], v[252:255], v[0:15]
	v_cvt_pk_bf16_f32 v188, v98, v99
	v_cvt_pk_bf16_f32 v189, v96, v97
	v_exp_f32_e32 v100, v108
	v_exp_f32_e32 v101, v109
	v_mfma_f32_32x32x16_bf16 v[16:31], v[172:175], v[216:219], v[16:31]
	v_exp_f32_e32 v96, v110
	v_exp_f32_e32 v97, v111
	v_cvt_pk_bf16_f32 v174, v100, v101
	v_cvt_pk_bf16_f32 v175, v96, v97
	s_add_i32 s7, s7, 1
	s_mov_b32 s27, s6
	s_mov_b32 s6, s10
	s_cmp_lg_u32 s55, s7
	s_mov_b32 s10, s26
	s_cbranch_scc1 .LBB0_316
; #define MFMA32(a, b, c) __builtin_amdgcn_mfma_f32_32x32x16_bf16(a, b, c, 0, 0, 0)
; template <bool SAFE>
; __device__ __forceinline__ void diff_core(const bf16* __restrict__ Kh, const bf16* __restrict__ Vh, const int NT, const bf16x8* qr, char* lds,
;                                           const int wid, const int lane_unused, f32x16* o, f32x16& lacc, float& l_reg) {
;     ...
;   pv_d0(o, vb0 + bp * SHM_V, pa0, pa1, pa2, pa3);
;   if constexpr (!SAFE) {
;     lacc = MFMA32(pa0, ones, lacc); lacc = MFMA32(pa1, ones, lacc); lacc = MFMA32(pa2, ones, lacc); lacc = MFMA32(pa3, ones, lacc); }
; __device__ __forceinline__ void diff_attn_item(const bf16* __restrict__ qkv, bf16* __restrict__ mix, const float* __restrict__ dg,
;                                int tok0  , int key0  , int seq, int head, float lam, float oscale, const int W) {
;     ...
;     bool bad = (FORCE_SAFE != 0);
; #pragma unroll
;     for (int r = 0; r < 16; ++r) bad = bad || !(lacc[r] < 1.0e30f);
;     if (lane == 0) flag_l[wid] = __any(bad) ? 1 : 0;
	s_waitcnt vmcnt(0)
	v_add_u32_e32 v168, s11, v211
	ds_read_b64_tr_b16 v[80:81], v168 offset:0
	ds_read_b64_tr_b16 v[82:83], v168 offset:0x800
	ds_read_b64_tr_b16 v[84:85], v168 offset:0x1000
	ds_read_b64_tr_b16 v[86:87], v168 offset:0x1800
	ds_read_b64_tr_b16 v[88:89], v168 offset:0x2000
	ds_read_b64_tr_b16 v[90:91], v168 offset:0x2800
	ds_read_b64_tr_b16 v[92:93], v168 offset:0x3000
	ds_read_b64_tr_b16 v[94:95], v168 offset:0x3800
	s_waitcnt lgkmcnt(0)
	s_waitcnt vmcnt(0)
	v_mov_b32_e32 v162, v182
	v_mov_b32_e32 v163, v183
	v_mov_b32_e32 v172, v186
	v_mov_b32_e32 v173, v187
	v_mov_b32_e32 v182, v178
	v_mov_b32_e32 v183, v179
	v_mov_b32_e32 v190, v174
	v_mov_b32_e32 v191, v175
	ds_read_b64_tr_b16 v[96:97], v168 offset:0x200
	ds_read_b64_tr_b16 v[98:99], v168 offset:0xa00
	ds_read_b64_tr_b16 v[100:101], v168 offset:0x1200
	ds_read_b64_tr_b16 v[102:103], v168 offset:0x1a00
	ds_read_b64_tr_b16 v[104:105], v168 offset:0x2200
	ds_read_b64_tr_b16 v[106:107], v168 offset:0x2a00
	ds_read_b64_tr_b16 v[108:109], v168 offset:0x3200
	ds_read_b64_tr_b16 v[110:111], v168 offset:0x3a00
	s_waitcnt lgkmcnt(0)
	ds_read_b64_tr_b16 v[112:113], v168 offset:0x400
	ds_read_b64_tr_b16 v[114:115], v168 offset:0xc00
	ds_read_b64_tr_b16 v[116:117], v168 offset:0x1400
	ds_read_b64_tr_b16 v[118:119], v168 offset:0x1c00
	ds_read_b64_tr_b16 v[120:121], v168 offset:0x2400
	ds_read_b64_tr_b16 v[122:123], v168 offset:0x2c00
	ds_read_b64_tr_b16 v[124:125], v168 offset:0x3400
	ds_read_b64_tr_b16 v[126:127], v168 offset:0x3c00
	s_waitcnt lgkmcnt(0)
	ds_read_b64_tr_b16 v[152:153], v168 offset:0x600
	ds_read_b64_tr_b16 v[154:155], v168 offset:0xe00
	ds_read_b64_tr_b16 v[156:157], v168 offset:0x1600
	ds_read_b64_tr_b16 v[158:159], v168 offset:0x1e00
	ds_read_b64_tr_b16 v[164:165], v168 offset:0x2600
	ds_read_b64_tr_b16 v[166:167], v168 offset:0x2e00
	ds_read_b64_tr_b16 v[174:175], v168 offset:0x3600
	ds_read_b64_tr_b16 v[176:177], v168 offset:0x3e00
	s_waitcnt lgkmcnt(0)
	v_mfma_f32_16x16x32_bf16 v[64:67], v[160:163], v[148:151], v[64:67]
	v_cmp_eq_u32_e32 vcc, 0, v200
	v_mfma_f32_32x32x16_bf16 v[48:63], v[160:163], v[80:83], v[48:63]
	v_mfma_f32_32x32x16_bf16 v[32:47], v[160:163], v[96:99], v[32:47]
	v_mfma_f32_32x32x16_bf16 v[0:15], v[160:163], v[112:115], v[0:15]
	v_mfma_f32_32x32x16_bf16 v[16:31], v[160:163], v[152:155], v[16:31]
	v_mfma_f32_16x16x32_bf16 v[64:67], v[170:173], v[148:151], v[64:67]
	v_mfma_f32_32x32x16_bf16 v[48:63], v[170:173], v[84:87], v[48:63]
	v_mfma_f32_32x32x16_bf16 v[32:47], v[170:173], v[100:103], v[32:47]
	v_mfma_f32_32x32x16_bf16 v[0:15], v[170:173], v[116:119], v[0:15]
	v_mfma_f32_32x32x16_bf16 v[16:31], v[170:173], v[156:159], v[16:31]
	v_mfma_f32_16x16x32_bf16 v[64:67], v[180:183], v[148:151], v[64:67]
	v_mfma_f32_32x32x16_bf16 v[48:63], v[180:183], v[88:91], v[48:63]
	v_mfma_f32_32x32x16_bf16 v[32:47], v[180:183], v[104:107], v[32:47]
	v_mfma_f32_32x32x16_bf16 v[0:15], v[180:183], v[120:123], v[0:15]
	v_mfma_f32_32x32x16_bf16 v[16:31], v[180:183], v[164:167], v[16:31]
	v_mfma_f32_16x16x32_bf16 v[64:67], v[188:191], v[148:151], v[64:67]
	v_mfma_f32_32x32x16_bf16 v[48:63], v[188:191], v[92:95], v[48:63]
	v_mfma_f32_32x32x16_bf16 v[32:47], v[188:191], v[108:111], v[32:47]
	v_mfma_f32_32x32x16_bf16 v[0:15], v[188:191], v[124:127], v[0:15]
	v_mfma_f32_32x32x16_bf16 v[16:31], v[188:191], v[174:177], v[16:31]
	v_and_b32_e32 v248, 15, v200
	v_lshrrev_b32_e32 v249, 4, v200
	v_and_b32_e32 v250, 1, v200
	v_lshlrev_b32_e32 v249, 4, v249
	v_lshl_add_u32 v249, v250, 6, v249
	v_add_u32_e32 v249, s62, v249
	v_cmp_gt_u32_e64 s[98:99], 2, v248
	v_lshl_add_u32 v250, v198, 4, s62
	s_nop 7
	s_and_saveexec_b64 s[100:101], s[98:99]
	ds_write_b128 v249, v[64:67]
	s_mov_b64 exec, s[100:101]
	s_waitcnt lgkmcnt(0)
	ds_read_b128 v[64:67], v250
	ds_read_b128 v[68:71], v250 offset:32
	ds_read_b128 v[72:75], v250 offset:64
	ds_read_b128 v[76:79], v250 offset:96
	s_waitcnt lgkmcnt(0)
	s_and_saveexec_b64 s[10:11], vcc
	s_cbranch_execz .LBB0_319
	s_nop 5
	v_cmp_ngt_f32_e32 vcc, s44, v64
	v_cmp_ngt_f32_e64 s[6:7], s44, v65
	s_or_b64 s[6:7], vcc, s[6:7]
	v_cmp_ngt_f32_e32 vcc, s44, v66
	s_or_b64 s[6:7], s[6:7], vcc
	v_cmp_ngt_f32_e32 vcc, s44, v67
	s_or_b64 s[6:7], s[6:7], vcc
	v_cmp_ngt_f32_e32 vcc, s44, v68
	s_or_b64 s[6:7], s[6:7], vcc
	v_cmp_ngt_f32_e32 vcc, s44, v69
	s_or_b64 s[6:7], s[6:7], vcc
	v_cmp_ngt_f32_e32 vcc, s44, v70
	s_or_b64 s[6:7], s[6:7], vcc
	v_cmp_ngt_f32_e32 vcc, s44, v71
	s_or_b64 s[6:7], s[6:7], vcc
	v_cmp_ngt_f32_e32 vcc, s44, v72
	s_or_b64 s[6:7], s[6:7], vcc
	v_cmp_ngt_f32_e32 vcc, s44, v73
	s_or_b64 s[6:7], s[6:7], vcc
	v_cmp_ngt_f32_e32 vcc, s44, v74
	s_or_b64 s[6:7], s[6:7], vcc
	v_cmp_ngt_f32_e32 vcc, s44, v75
	s_or_b64 s[6:7], s[6:7], vcc
	v_cmp_ngt_f32_e32 vcc, s44, v76
	s_or_b64 s[6:7], s[6:7], vcc
	v_cmp_ngt_f32_e32 vcc, s44, v77
	s_or_b64 s[6:7], s[6:7], vcc
	v_cmp_ngt_f32_e32 vcc, s44, v78
	s_or_b64 s[6:7], s[6:7], vcc
	v_cmp_ngt_f32_e32 vcc, s44, v79
	s_or_b64 s[6:7], s[6:7], vcc
	v_cndmask_b32_e64 v80, 0, 1, s[6:7]
	v_cmp_ne_u32_e32 vcc, 0, v80
	s_cmp_lg_u64 vcc, 0
	s_cselect_b64 s[6:7], -1, 0
	v_cndmask_b32_e64 v80, 0, 1, s[6:7]
	v_readlane_b32 s6, v246, 17
	s_nop 1
	v_mov_b32_e32 v81, s6
	ds_write_b32 v81, v80
